# B mixer: fold log2(e) into the bf16 Q prescale (q*0.125*log2e) and drop the 64 per-tile f32 scale multiplies
# speedup vs baseline: 1.0074x; 1.0001x over previous
.LBB0_587:
	s_and_b64 vcc, exec, s[14:15]
	s_cbranch_vccnz .LBB0_589
	v_lshlrev_b32_e32 v0, 1, v156
	v_lshl_add_u64 v[2:3], s[40:41], 0, v[0:1]
	v_lshlrev_b32_e32 v18, 1, v158
	v_mov_b32_e32 v19, v1
	v_lshl_add_u64 v[2:3], v[2:3], 0, v[18:19]
	global_load_dwordx4 v[6:9], v[2:3], off
	global_load_dwordx4 v[10:13], v[2:3], off offset:32
	global_load_dwordx4 v[14:17], v[2:3], off offset:64
	s_nop 0
	global_load_dwordx4 v[2:5], v[2:3], off offset:96
	v_lshl_add_u64 v[20:21], s[76:77], 0, v[0:1]
	v_lshl_add_u64 v[18:19], v[20:21], 0, v[18:19]
	global_load_dwordx4 v[92:95], v[18:19], off
	global_load_dwordx4 v[88:91], v[18:19], off offset:32
	global_load_dwordx4 v[84:87], v[18:19], off offset:64
	global_load_dwordx4 v[80:83], v[18:19], off offset:96
	s_waitcnt vmcnt(7)
	v_lshlrev_b32_e32 v0, 16, v6
	v_mul_f32_e32 v0, 0x3e38aa3b, v0
	v_and_b32_e32 v6, 0xffff0000, v6
	v_mul_f32_e32 v6, 0x3e38aa3b, v6
	v_cvt_pk_bf16_f32 v96, v0, v6
	v_lshlrev_b32_e32 v0, 16, v7
	v_mul_f32_e32 v0, 0x3e38aa3b, v0
	v_and_b32_e32 v6, 0xffff0000, v7
	v_mul_f32_e32 v6, 0x3e38aa3b, v6
	v_cvt_pk_bf16_f32 v97, v0, v6
	v_lshlrev_b32_e32 v0, 16, v8
	v_mul_f32_e32 v0, 0x3e38aa3b, v0
	v_and_b32_e32 v6, 0xffff0000, v8
	v_mul_f32_e32 v6, 0x3e38aa3b, v6
	v_cvt_pk_bf16_f32 v98, v0, v6
	v_lshlrev_b32_e32 v0, 16, v9
	v_mul_f32_e32 v0, 0x3e38aa3b, v0
	v_and_b32_e32 v6, 0xffff0000, v9
	v_mul_f32_e32 v6, 0x3e38aa3b, v6
	v_cvt_pk_bf16_f32 v99, v0, v6
	s_waitcnt vmcnt(6)
	v_lshlrev_b32_e32 v0, 16, v10
	v_mul_f32_e32 v0, 0x3e38aa3b, v0
	v_and_b32_e32 v6, 0xffff0000, v10
	v_mul_f32_e32 v6, 0x3e38aa3b, v6
	v_cvt_pk_bf16_f32 v100, v0, v6
	v_lshlrev_b32_e32 v0, 16, v11
	v_mul_f32_e32 v0, 0x3e38aa3b, v0
	v_and_b32_e32 v6, 0xffff0000, v11
	v_mul_f32_e32 v6, 0x3e38aa3b, v6
	v_cvt_pk_bf16_f32 v101, v0, v6
	v_lshlrev_b32_e32 v0, 16, v12
	v_mul_f32_e32 v0, 0x3e38aa3b, v0
	v_and_b32_e32 v6, 0xffff0000, v12
	v_mul_f32_e32 v6, 0x3e38aa3b, v6
	v_cvt_pk_bf16_f32 v102, v0, v6
	v_lshlrev_b32_e32 v0, 16, v13
	v_mul_f32_e32 v0, 0x3e38aa3b, v0
	v_and_b32_e32 v6, 0xffff0000, v13
	v_mul_f32_e32 v6, 0x3e38aa3b, v6
	v_cvt_pk_bf16_f32 v103, v0, v6
	s_waitcnt vmcnt(5)
	v_lshlrev_b32_e32 v0, 16, v14
	v_mul_f32_e32 v0, 0x3e38aa3b, v0
	v_and_b32_e32 v6, 0xffff0000, v14
	v_mul_f32_e32 v6, 0x3e38aa3b, v6
	v_cvt_pk_bf16_f32 v104, v0, v6
	v_lshlrev_b32_e32 v0, 16, v15
	v_mul_f32_e32 v0, 0x3e38aa3b, v0
	v_and_b32_e32 v6, 0xffff0000, v15
	v_mul_f32_e32 v6, 0x3e38aa3b, v6
	v_cvt_pk_bf16_f32 v105, v0, v6
	v_lshlrev_b32_e32 v0, 16, v16
	v_mul_f32_e32 v0, 0x3e38aa3b, v0
	v_and_b32_e32 v6, 0xffff0000, v16
	v_mul_f32_e32 v6, 0x3e38aa3b, v6
	v_cvt_pk_bf16_f32 v106, v0, v6
	v_lshlrev_b32_e32 v0, 16, v17
	v_mul_f32_e32 v0, 0x3e38aa3b, v0
	v_and_b32_e32 v6, 0xffff0000, v17
	v_mul_f32_e32 v6, 0x3e38aa3b, v6
	v_cvt_pk_bf16_f32 v107, v0, v6
	s_waitcnt vmcnt(4)
	v_lshlrev_b32_e32 v0, 16, v2
	v_and_b32_e32 v2, 0xffff0000, v2
	v_mul_f32_e32 v0, 0x3e38aa3b, v0
	v_mul_f32_e32 v2, 0x3e38aa3b, v2
	v_cvt_pk_bf16_f32 v108, v0, v2
	v_lshlrev_b32_e32 v0, 16, v3
	v_and_b32_e32 v2, 0xffff0000, v3
	v_mul_f32_e32 v0, 0x3e38aa3b, v0
	v_mul_f32_e32 v2, 0x3e38aa3b, v2
	v_cvt_pk_bf16_f32 v109, v0, v2
	v_lshlrev_b32_e32 v0, 16, v4
	v_and_b32_e32 v2, 0xffff0000, v4
	v_mul_f32_e32 v0, 0x3e38aa3b, v0
	v_mul_f32_e32 v2, 0x3e38aa3b, v2
	v_cvt_pk_bf16_f32 v110, v0, v2
	v_lshlrev_b32_e32 v0, 16, v5
	v_and_b32_e32 v2, 0xffff0000, v5
	v_mul_f32_e32 v0, 0x3e38aa3b, v0
	v_mul_f32_e32 v2, 0x3e38aa3b, v2
	v_cvt_pk_bf16_f32 v111, v0, v2

.LBB0_657:
	s_andn2_b64 vcc, exec, s[0:1]
	s_mov_b64 s[16:17], -1
	s_cbranch_vccnz .LBB0_668
	s_add_i32 s51, s13, s23
	s_sub_i32 s0, s51, 64
	s_cmp_ge_i32 s0, s53
	s_mov_b64 s[16:17], 0
	s_cbranch_scc1 .LBB0_668
	v_add3_u32 v0, s28, v209, v210
	ds_read_b128 v[2:5], v0
	s_sub_i32 s0, s51, 63
	s_cmp_lt_i32 s0, s20
	s_cselect_b64 s[62:63], -1, 0
	s_cmp_ge_i32 s0, s20
	v_mov_b32_e32 v15, 0
	s_waitcnt lgkmcnt(0)
	v_mfma_f32_32x32x16_bf16 v[48:63], v[2:5], v[96:99], 0
	ds_read_b128 v[2:5], v0 offset:4608
	s_waitcnt lgkmcnt(0)
	v_mfma_f32_32x32x16_bf16 v[64:79], v[2:5], v[96:99], 0
	ds_read_b128 v[2:5], v0 offset:32
	s_waitcnt lgkmcnt(0)
	v_mfma_f32_32x32x16_bf16 v[48:63], v[2:5], v[100:103], v[48:63]
	ds_read_b128 v[2:5], v0 offset:4640
	s_waitcnt lgkmcnt(0)
	v_mfma_f32_32x32x16_bf16 v[64:79], v[2:5], v[100:103], v[64:79]
	ds_read_b128 v[2:5], v0 offset:64
	s_waitcnt lgkmcnt(0)
	v_mfma_f32_32x32x16_bf16 v[48:63], v[2:5], v[104:107], v[48:63]
	ds_read_b128 v[2:5], v0 offset:4672
	s_waitcnt lgkmcnt(0)
	v_mfma_f32_32x32x16_bf16 v[64:79], v[2:5], v[104:107], v[64:79]
	ds_read_b128 v[2:5], v0 offset:96
	s_waitcnt lgkmcnt(0)
	v_mfma_f32_32x32x16_bf16 v[48:63], v[2:5], v[108:111], v[48:63]
	ds_read_b128 v[2:5], v0 offset:4704
	s_waitcnt lgkmcnt(0)
	v_mfma_f32_32x32x16_bf16 v[64:79], v[2:5], v[108:111], v[64:79]
	s_cbranch_scc1 .LBB0_663
	s_nop 10
	v_min_f32_e32 v0, 0x42a00000, v64
	v_exp_f32_e32 v2, v0
	v_min_f32_e32 v0, 0x42a00000, v65
	v_exp_f32_e32 v3, v0
	v_add_f32_e32 v0, 1.0, v2
	v_rcp_f32_e32 v6, v0
	v_add_f32_e32 v0, 1.0, v3
	v_rcp_f32_e32 v7, v0
	v_min_f32_e32 v5, 0x42a00000, v67
	v_min_f32_e32 v10, 0x42a00000, v69
	v_min_f32_e32 v0, 0x42a00000, v66
	v_exp_f32_e32 v8, v5
	v_exp_f32_e32 v12, v10
	v_exp_f32_e32 v0, v0
	v_min_f32_e32 v5, 0x42a00000, v68
	v_min_f32_e32 v10, 0x42a00000, v70
	v_exp_f32_e32 v9, v5
	v_exp_f32_e32 v13, v10
	v_add_f32_e32 v4, 1.0, v0
	v_add_f32_e32 v10, 1.0, v12
	v_rcp_f32_e32 v180, v4
	v_add_f32_e32 v4, 1.0, v8
	v_add_f32_e32 v5, 1.0, v9
	v_rcp_f32_e32 v66, v10
	v_add_f32_e32 v10, 1.0, v13
	v_rcp_f32_e32 v4, v4
	v_rcp_f32_e32 v5, v5
	v_rcp_f32_e32 v67, v10
	v_min_f32_e32 v10, 0x42a00000, v71
	v_exp_f32_e32 v65, v10
	v_pk_mul_f32 v[10:11], v[8:9], v[4:5]
	v_pk_mul_f32 v[8:9], v[12:13], v[66:67]
	v_min_f32_e32 v13, 0x42a00000, v72
	v_exp_f32_e32 v14, v13
	v_min_f32_e32 v13, 0x42a00000, v73
	v_exp_f32_e32 v15, v13
	v_add_f32_e32 v12, 1.0, v65
	v_rcp_f32_e32 v13, v12
	v_add_f32_e32 v12, 1.0, v14
	v_rcp_f32_e32 v64, v12
	v_add_f32_e32 v12, 1.0, v15
	v_rcp_f32_e32 v68, v12
	v_min_f32_e32 v12, 0x42a00000, v74
	v_exp_f32_e32 v12, v12
	v_mul_f32_e32 v181, v65, v13
	v_mov_b32_e32 v65, v68
	v_pk_mul_f32 v[14:15], v[14:15], v[64:65]
	v_add_f32_e32 v65, 1.0, v12
	v_rcp_f32_e32 v70, v65
	v_min_f32_e32 v65, 0x42a00000, v75
	v_exp_f32_e32 v72, v65
	v_min_f32_e32 v65, 0x42a00000, v76
	v_exp_f32_e32 v73, v65
	v_mul_f32_e32 v182, v12, v70
	v_add_f32_e32 v12, 1.0, v72
	v_rcp_f32_e32 v74, v12
	v_add_f32_e32 v12, 1.0, v73
	v_rcp_f32_e32 v65, v12
	v_min_f32_e32 v12, 0x42a00000, v77
	v_exp_f32_e32 v76, v12
	v_min_f32_e32 v12, 0x42a00000, v78
	v_exp_f32_e32 v77, v12
	v_add_f32_e32 v12, 1.0, v76
	v_rcp_f32_e32 v69, v12
	v_mov_b32_e32 v75, v65
	v_add_f32_e32 v12, 1.0, v77
	v_rcp_f32_e32 v71, v12
	v_min_f32_e32 v12, 0x42a00000, v79
	v_exp_f32_e32 v12, v12
	v_pk_mul_f32 v[78:79], v[72:73], v[74:75]
	v_mov_b32_e32 v72, v69
	v_mov_b32_e32 v73, v71
	v_add_f32_e32 v75, 1.0, v12
	v_rcp_f32_e32 v75, v75
	s_add_i32 s0, s51, -1
	v_pk_mul_f32 v[2:3], v[2:3], v[6:7]
	v_mul_f32_e32 v0, v0, v180
	v_pk_mul_f32 v[76:77], v[76:77], v[72:73]
	s_cmp_lt_i32 s0, s20
	v_mul_f32_e32 v183, v12, v75
	s_cbranch_scc1 .LBB0_662
	v_add3_u32 v12, s21, v151, 64
	v_cmp_lt_i32_e32 vcc, 0, v12
	v_cmp_lt_i32_e64 s[0:1], 1, v12
	v_cmp_lt_i32_e64 s[18:19], 24, v12
	v_cndmask_b32_e32 v6, 1.0, v6, vcc
	v_cndmask_b32_e32 v2, 0, v2, vcc
	v_cmp_lt_i32_e32 vcc, 2, v12
	v_cndmask_b32_e64 v7, 1.0, v7, s[0:1]
	v_cndmask_b32_e64 v3, 0, v3, s[0:1]
	v_cndmask_b32_e32 v180, 1.0, v180, vcc
	v_cndmask_b32_e32 v0, 0, v0, vcc
	v_cmp_lt_i32_e32 vcc, 3, v12
	v_cmp_lt_i32_e64 s[0:1], 8, v12
	v_cmp_lt_i32_e64 s[16:17], 18, v12
	v_cndmask_b32_e32 v4, 1.0, v4, vcc
	v_cndmask_b32_e32 v10, 0, v10, vcc
	v_cmp_lt_i32_e32 vcc, 9, v12
	v_cndmask_b32_e64 v5, 1.0, v5, s[0:1]
	v_cndmask_b32_e64 v11, 0, v11, s[0:1]
	v_cndmask_b32_e32 v66, 1.0, v66, vcc
	v_cndmask_b32_e32 v8, 0, v8, vcc
	v_cmp_lt_i32_e32 vcc, 11, v12
	v_cmp_lt_i32_e64 s[0:1], 10, v12
	v_cndmask_b32_e64 v65, 1.0, v65, s[18:19]
	v_cndmask_b32_e32 v13, 1.0, v13, vcc
	v_cndmask_b32_e32 v181, 0, v181, vcc
	v_cmp_lt_i32_e32 vcc, 17, v12
	v_cndmask_b32_e64 v67, 1.0, v67, s[0:1]
	v_cndmask_b32_e64 v9, 0, v9, s[0:1]
	v_cndmask_b32_e32 v15, 0, v15, vcc
	v_cmp_lt_i32_e64 s[0:1], 16, v12
	v_cndmask_b32_e32 v68, 1.0, v68, vcc
	v_cmp_lt_i32_e32 vcc, 26, v12
	v_cndmask_b32_e64 v14, 0, v14, s[0:1]
	v_cndmask_b32_e64 v64, 1.0, v64, s[0:1]
	v_cndmask_b32_e64 v79, 0, v79, s[18:19]
	v_cmp_lt_i32_e64 s[0:1], 19, v12
	v_cmp_lt_i32_e64 s[18:19], 25, v12
	v_cndmask_b32_e32 v71, 1.0, v71, vcc
	v_cndmask_b32_e32 v77, 0, v77, vcc
	v_cmp_lt_i32_e32 vcc, 27, v12
	v_cndmask_b32_e64 v182, 0, v182, s[16:17]
	v_cndmask_b32_e64 v78, 0, v78, s[0:1]
	v_cndmask_b32_e64 v69, 1.0, v69, s[18:19]
	v_cndmask_b32_e64 v70, 1.0, v70, s[16:17]
	v_cndmask_b32_e64 v76, 0, v76, s[18:19]
	v_cndmask_b32_e32 v75, 1.0, v75, vcc
	v_cndmask_b32_e64 v74, 1.0, v74, s[0:1]
	v_cndmask_b32_e32 v183, 0, v183, vcc

.LBB0_664:
	v_min_f32_e32 v2, 0x42a00000, v48
	v_exp_f32_e32 v2, v2
	v_min_f32_e32 v3, 0x42a00000, v49
	v_exp_f32_e32 v3, v3
	v_add_f32_e32 v4, 1.0, v2
	v_rcp_f32_e32 v12, v4
	v_min_f32_e32 v4, 0x42a00000, v50
	v_exp_f32_e32 v4, v4
	v_mul_f32_e32 v75, v2, v12
	v_min_f32_e32 v2, 0x42a00000, v51
	v_exp_f32_e32 v6, v2
	v_add_f32_e32 v5, 1.0, v3
	v_rcp_f32_e32 v51, v5
	v_add_f32_e32 v2, 1.0, v4
	v_rcp_f32_e32 v76, v2
	v_add_f32_e32 v2, 1.0, v6
	v_min_f32_e32 v5, 0x42a00000, v52
	v_min_f32_e32 v7, 0x42a00000, v53
	v_rcp_f32_e32 v2, v2
	v_exp_f32_e32 v5, v5
	v_exp_f32_e32 v8, v7
	v_min_f32_e32 v7, 0x42a00000, v54
	v_exp_f32_e32 v9, v7
	v_mul_f32_e32 v52, v3, v51
	v_mul_f32_e32 v3, v6, v2
	v_add_f32_e32 v6, 1.0, v5
	v_rcp_f32_e32 v77, v6
	v_add_f32_e32 v6, 1.0, v8
	v_rcp_f32_e32 v78, v6
	v_add_f32_e32 v6, 1.0, v9
	v_rcp_f32_e32 v79, v6
	v_mul_f32_e32 v7, v5, v77
	v_min_f32_e32 v11, 0x42a00000, v57
	v_mul_f32_e32 v5, v9, v79
	v_min_f32_e32 v9, 0x42a00000, v56
	v_exp_f32_e32 v9, v9
	v_exp_f32_e32 v13, v11
	v_min_f32_e32 v6, 0x42a00000, v55
	v_exp_f32_e32 v10, v6
	v_min_f32_e32 v49, 0x42a00000, v59
	v_add_f32_e32 v11, 1.0, v9
	v_exp_f32_e32 v50, v49
	v_rcp_f32_e32 v57, v11
	v_add_f32_e32 v11, 1.0, v13
	v_min_f32_e32 v49, 0x42a00000, v60
	v_rcp_f32_e32 v181, v11
	v_exp_f32_e32 v53, v49
	v_mul_f32_e32 v6, v8, v78
	v_add_f32_e32 v8, 1.0, v10
	v_min_f32_e32 v11, 0x42a00000, v58
	v_rcp_f32_e32 v8, v8
	v_exp_f32_e32 v48, v11
	v_add_f32_e32 v49, 1.0, v53
	v_rcp_f32_e32 v58, v49
	v_mul_f32_e32 v11, v10, v8
	v_mul_f32_e32 v10, v9, v57
	v_mul_f32_e32 v9, v13, v181
	v_add_f32_e32 v13, 1.0, v48
	v_min_f32_e32 v49, 0x42a00000, v61
	v_rcp_f32_e32 v59, v13
	v_exp_f32_e32 v54, v49
	v_add_f32_e32 v13, 1.0, v50
	v_rcp_f32_e32 v13, v13
	v_mul_f32_e32 v49, v48, v59
	v_mul_f32_e32 v48, v53, v58
	v_add_f32_e32 v53, 1.0, v54
	v_rcp_f32_e32 v60, v53
	v_min_f32_e32 v53, 0x42a00000, v62
	v_exp_f32_e32 v56, v53
	v_min_f32_e32 v53, 0x42a00000, v63
	v_exp_f32_e32 v62, v53
	v_add_f32_e32 v53, 1.0, v56
	v_rcp_f32_e32 v61, v53
	v_mul_f32_e32 v53, v54, v60
	v_add_f32_e32 v54, 1.0, v62
	v_rcp_f32_e32 v55, v54
	s_sub_i32 s0, s51, 33
	v_mul_f32_e32 v4, v4, v76
	v_mul_f32_e32 v50, v50, v13
	v_mul_f32_e32 v54, v56, v61
	s_cmp_lt_i32 s0, s20
	v_mul_f32_e32 v56, v62, v55
	s_cbranch_scc1 .LBB0_666
	v_add3_u32 v62, s21, v178, 64
	v_cmp_lt_i32_e32 vcc, 0, v62
	s_nop 1
	v_cndmask_b32_e32 v12, 1.0, v12, vcc
	v_cndmask_b32_e32 v75, 0, v75, vcc
	v_cmp_lt_i32_e32 vcc, 1, v62
	s_nop 1
	v_cndmask_b32_e32 v51, 1.0, v51, vcc
	v_cndmask_b32_e32 v52, 0, v52, vcc
	v_cmp_lt_i32_e32 vcc, 2, v62
	s_nop 1
	v_cndmask_b32_e32 v76, 1.0, v76, vcc
	v_cndmask_b32_e32 v4, 0, v4, vcc
	v_cmp_lt_i32_e32 vcc, 3, v62
	s_nop 1
	v_cndmask_b32_e32 v2, 1.0, v2, vcc
	v_cndmask_b32_e32 v3, 0, v3, vcc
	v_cmp_lt_i32_e32 vcc, 8, v62
	s_nop 1
	v_cndmask_b32_e32 v77, 1.0, v77, vcc
	v_cndmask_b32_e32 v7, 0, v7, vcc
	v_cmp_lt_i32_e32 vcc, 9, v62
	s_nop 1
	v_cndmask_b32_e32 v78, 1.0, v78, vcc
	v_cndmask_b32_e32 v6, 0, v6, vcc
	v_cmp_lt_i32_e32 vcc, 10, v62
	s_nop 1
	v_cndmask_b32_e32 v79, 1.0, v79, vcc
	v_cndmask_b32_e32 v5, 0, v5, vcc
	v_cmp_lt_i32_e32 vcc, 11, v62
	s_nop 1
	v_cndmask_b32_e32 v8, 1.0, v8, vcc
	v_cndmask_b32_e32 v11, 0, v11, vcc
	v_cmp_lt_i32_e32 vcc, 16, v62
	s_nop 1
	v_cndmask_b32_e32 v57, 1.0, v57, vcc
	v_cndmask_b32_e32 v10, 0, v10, vcc
	v_cmp_lt_i32_e32 vcc, 17, v62
	s_nop 1
	v_cndmask_b32_e32 v181, 1.0, v181, vcc
	v_cndmask_b32_e32 v9, 0, v9, vcc
	v_cmp_lt_i32_e32 vcc, 18, v62
	s_nop 1
	v_cndmask_b32_e32 v59, 1.0, v59, vcc
	v_cndmask_b32_e32 v49, 0, v49, vcc
	v_cmp_lt_i32_e32 vcc, 19, v62
	s_nop 1
	v_cndmask_b32_e32 v13, 1.0, v13, vcc
	v_cndmask_b32_e32 v50, 0, v50, vcc
	v_cmp_lt_i32_e32 vcc, 24, v62
	s_nop 1
	v_cndmask_b32_e32 v58, 1.0, v58, vcc
	v_cndmask_b32_e32 v48, 0, v48, vcc
	v_cmp_lt_i32_e32 vcc, 25, v62
	s_nop 1
	v_cndmask_b32_e32 v60, 1.0, v60, vcc
	v_cndmask_b32_e32 v53, 0, v53, vcc
	v_cmp_lt_i32_e32 vcc, 26, v62
	s_nop 1
	v_cndmask_b32_e32 v61, 1.0, v61, vcc
	v_cndmask_b32_e32 v54, 0, v54, vcc
	v_cmp_lt_i32_e32 vcc, 27, v62
	s_nop 1
	v_cndmask_b32_e32 v55, 1.0, v55, vcc
	v_cndmask_b32_e32 v56, 0, v56, vcc

.LBB0_668:
	s_cmp_gt_i32 s25, s8
	s_cselect_b64 s[0:1], -1, 0
	s_and_b64 s[0:1], s[0:1], s[42:43]
	s_andn2_b64 vcc, exec, s[0:1]
	s_cbranch_vccnz .LBB0_675
	s_xor_b64 s[0:1], s[16:17], -1
	s_andn2_b64 vcc, exec, s[0:1]
	s_mov_b64 s[16:17], -1
	s_cbranch_vccnz .LBB0_675
	s_add_i32 s25, s13, s23
	s_add_i32 s0, s25, 0xffffff80
	s_cmp_ge_i32 s0, s53
	s_mov_b64 s[16:17], 0
	s_cbranch_scc1 .LBB0_675
	v_add3_u32 v0, s26, v209, v210
	ds_read_b128 v[2:5], v0
	s_add_i32 s0, s25, 0xffffff81
	s_cmp_lt_i32 s0, s20
	s_cselect_b64 s[62:63], -1, 0
	s_cmp_ge_i32 s0, s20
	v_mov_b32_e32 v15, 0
	s_waitcnt lgkmcnt(0)
	v_mfma_f32_32x32x16_bf16 v[48:63], v[2:5], v[96:99], 0
	ds_read_b128 v[2:5], v0 offset:4608
	s_waitcnt lgkmcnt(0)
	v_mfma_f32_32x32x16_bf16 v[64:79], v[2:5], v[96:99], 0
	ds_read_b128 v[2:5], v0 offset:32
	s_waitcnt lgkmcnt(0)
	v_mfma_f32_32x32x16_bf16 v[48:63], v[2:5], v[100:103], v[48:63]
	ds_read_b128 v[2:5], v0 offset:4640
	s_waitcnt lgkmcnt(0)
	v_mfma_f32_32x32x16_bf16 v[64:79], v[2:5], v[100:103], v[64:79]
	ds_read_b128 v[2:5], v0 offset:64
	s_waitcnt lgkmcnt(0)
	v_mfma_f32_32x32x16_bf16 v[48:63], v[2:5], v[104:107], v[48:63]
	ds_read_b128 v[2:5], v0 offset:4672
	s_waitcnt lgkmcnt(0)
	v_mfma_f32_32x32x16_bf16 v[64:79], v[2:5], v[104:107], v[64:79]
	ds_read_b128 v[2:5], v0 offset:96
	s_waitcnt lgkmcnt(0)
	v_mfma_f32_32x32x16_bf16 v[48:63], v[2:5], v[108:111], v[48:63]
	ds_read_b128 v[2:5], v0 offset:4704
	s_waitcnt lgkmcnt(0)
	v_mfma_f32_32x32x16_bf16 v[64:79], v[2:5], v[108:111], v[64:79]
	s_cbranch_scc1 .LBB0_677
	s_nop 10
	v_min_f32_e32 v0, 0x42a00000, v64
	v_exp_f32_e32 v2, v0
	v_min_f32_e32 v0, 0x42a00000, v65
	v_exp_f32_e32 v3, v0
	v_add_f32_e32 v0, 1.0, v2
	v_rcp_f32_e32 v6, v0
	v_add_f32_e32 v0, 1.0, v3
	v_rcp_f32_e32 v7, v0
	v_min_f32_e32 v5, 0x42a00000, v67
	v_min_f32_e32 v10, 0x42a00000, v69
	v_min_f32_e32 v0, 0x42a00000, v66
	v_exp_f32_e32 v8, v5
	v_exp_f32_e32 v12, v10
	v_exp_f32_e32 v0, v0
	v_min_f32_e32 v5, 0x42a00000, v68
	v_min_f32_e32 v10, 0x42a00000, v70
	v_exp_f32_e32 v9, v5
	v_exp_f32_e32 v13, v10
	v_add_f32_e32 v4, 1.0, v0
	v_add_f32_e32 v10, 1.0, v12
	v_rcp_f32_e32 v180, v4
	v_add_f32_e32 v4, 1.0, v8
	v_add_f32_e32 v5, 1.0, v9
	v_rcp_f32_e32 v66, v10
	v_add_f32_e32 v10, 1.0, v13
	v_rcp_f32_e32 v4, v4
	v_rcp_f32_e32 v5, v5
	v_rcp_f32_e32 v67, v10
	v_min_f32_e32 v10, 0x42a00000, v71
	v_exp_f32_e32 v65, v10
	v_pk_mul_f32 v[10:11], v[8:9], v[4:5]
	v_pk_mul_f32 v[8:9], v[12:13], v[66:67]
	v_min_f32_e32 v13, 0x42a00000, v72
	v_exp_f32_e32 v14, v13
	v_min_f32_e32 v13, 0x42a00000, v73
	v_exp_f32_e32 v15, v13
	v_add_f32_e32 v12, 1.0, v65
	v_rcp_f32_e32 v13, v12
	v_add_f32_e32 v12, 1.0, v14
	v_rcp_f32_e32 v64, v12
	v_add_f32_e32 v12, 1.0, v15
	v_rcp_f32_e32 v68, v12
	v_min_f32_e32 v12, 0x42a00000, v74
	v_exp_f32_e32 v12, v12
	v_mul_f32_e32 v181, v65, v13
	v_mov_b32_e32 v65, v68
	v_pk_mul_f32 v[14:15], v[14:15], v[64:65]
	v_add_f32_e32 v65, 1.0, v12
	v_rcp_f32_e32 v70, v65
	v_min_f32_e32 v65, 0x42a00000, v75
	v_exp_f32_e32 v72, v65
	v_min_f32_e32 v65, 0x42a00000, v76
	v_exp_f32_e32 v73, v65
	v_mul_f32_e32 v182, v12, v70
	v_add_f32_e32 v12, 1.0, v72
	v_rcp_f32_e32 v74, v12
	v_add_f32_e32 v12, 1.0, v73
	v_rcp_f32_e32 v65, v12
	v_min_f32_e32 v12, 0x42a00000, v77
	v_exp_f32_e32 v76, v12
	v_min_f32_e32 v12, 0x42a00000, v78
	v_exp_f32_e32 v77, v12
	v_add_f32_e32 v12, 1.0, v76
	v_rcp_f32_e32 v69, v12
	v_mov_b32_e32 v75, v65
	v_add_f32_e32 v12, 1.0, v77
	v_rcp_f32_e32 v71, v12
	v_min_f32_e32 v12, 0x42a00000, v79
	v_exp_f32_e32 v12, v12
	v_pk_mul_f32 v[78:79], v[72:73], v[74:75]
	v_mov_b32_e32 v72, v69
	v_mov_b32_e32 v73, v71
	v_add_f32_e32 v75, 1.0, v12
	v_rcp_f32_e32 v75, v75
	s_add_i32 s0, s25, 0xffffffbf
	v_pk_mul_f32 v[2:3], v[2:3], v[6:7]
	v_mul_f32_e32 v0, v0, v180
	v_pk_mul_f32 v[76:77], v[76:77], v[72:73]
	s_cmp_lt_i32 s0, s20
	v_mul_f32_e32 v183, v12, v75
	s_cbranch_scc1 .LBB0_674
	v_add_u32_e32 v12, s21, v151
	v_add_u32_e32 v12, 0x80, v12
	v_cmp_lt_i32_e32 vcc, 0, v12
	v_cmp_lt_i32_e64 s[0:1], 1, v12
	v_cmp_lt_i32_e64 s[18:19], 24, v12
	v_cndmask_b32_e32 v6, 1.0, v6, vcc
	v_cndmask_b32_e32 v2, 0, v2, vcc
	v_cmp_lt_i32_e32 vcc, 2, v12
	v_cndmask_b32_e64 v7, 1.0, v7, s[0:1]
	v_cndmask_b32_e64 v3, 0, v3, s[0:1]
	v_cndmask_b32_e32 v180, 1.0, v180, vcc
	v_cndmask_b32_e32 v0, 0, v0, vcc
	v_cmp_lt_i32_e32 vcc, 3, v12
	v_cmp_lt_i32_e64 s[0:1], 8, v12
	v_cmp_lt_i32_e64 s[16:17], 18, v12
	v_cndmask_b32_e32 v4, 1.0, v4, vcc
	v_cndmask_b32_e32 v10, 0, v10, vcc
	v_cmp_lt_i32_e32 vcc, 9, v12
	v_cndmask_b32_e64 v5, 1.0, v5, s[0:1]
	v_cndmask_b32_e64 v11, 0, v11, s[0:1]
	v_cndmask_b32_e32 v66, 1.0, v66, vcc
	v_cndmask_b32_e32 v8, 0, v8, vcc
	v_cmp_lt_i32_e32 vcc, 11, v12
	v_cmp_lt_i32_e64 s[0:1], 10, v12
	v_cndmask_b32_e64 v65, 1.0, v65, s[18:19]
	v_cndmask_b32_e32 v13, 1.0, v13, vcc
	v_cndmask_b32_e32 v181, 0, v181, vcc
	v_cmp_lt_i32_e32 vcc, 17, v12
	v_cndmask_b32_e64 v67, 1.0, v67, s[0:1]
	v_cndmask_b32_e64 v9, 0, v9, s[0:1]
	v_cndmask_b32_e32 v15, 0, v15, vcc
	v_cmp_lt_i32_e64 s[0:1], 16, v12
	v_cndmask_b32_e32 v68, 1.0, v68, vcc
	v_cmp_lt_i32_e32 vcc, 26, v12
	v_cndmask_b32_e64 v14, 0, v14, s[0:1]
	v_cndmask_b32_e64 v64, 1.0, v64, s[0:1]
	v_cndmask_b32_e64 v79, 0, v79, s[18:19]
	v_cmp_lt_i32_e64 s[0:1], 19, v12
	v_cmp_lt_i32_e64 s[18:19], 25, v12
	v_cndmask_b32_e32 v71, 1.0, v71, vcc
	v_cndmask_b32_e32 v77, 0, v77, vcc
	v_cmp_lt_i32_e32 vcc, 27, v12
	v_cndmask_b32_e64 v182, 0, v182, s[16:17]
	v_cndmask_b32_e64 v78, 0, v78, s[0:1]
	v_cndmask_b32_e64 v69, 1.0, v69, s[18:19]
	v_cndmask_b32_e64 v70, 1.0, v70, s[16:17]
	v_cndmask_b32_e64 v76, 0, v76, s[18:19]
	v_cndmask_b32_e32 v75, 1.0, v75, vcc
	v_cndmask_b32_e64 v74, 1.0, v74, s[0:1]
	v_cndmask_b32_e32 v183, 0, v183, vcc

.LBB0_678:
	v_min_f32_e32 v2, 0x42a00000, v48
	v_exp_f32_e32 v2, v2
	v_min_f32_e32 v3, 0x42a00000, v49
	v_exp_f32_e32 v3, v3
	v_add_f32_e32 v4, 1.0, v2
	v_rcp_f32_e32 v12, v4
	v_min_f32_e32 v4, 0x42a00000, v50
	v_exp_f32_e32 v4, v4
	v_mul_f32_e32 v75, v2, v12
	v_min_f32_e32 v2, 0x42a00000, v51
	v_exp_f32_e32 v6, v2
	v_add_f32_e32 v5, 1.0, v3
	v_rcp_f32_e32 v51, v5
	v_add_f32_e32 v2, 1.0, v4
	v_rcp_f32_e32 v76, v2
	v_add_f32_e32 v2, 1.0, v6
	v_min_f32_e32 v5, 0x42a00000, v52
	v_min_f32_e32 v7, 0x42a00000, v53
	v_rcp_f32_e32 v2, v2
	v_exp_f32_e32 v5, v5
	v_exp_f32_e32 v8, v7
	v_min_f32_e32 v7, 0x42a00000, v54
	v_exp_f32_e32 v9, v7
	v_mul_f32_e32 v52, v3, v51
	v_mul_f32_e32 v3, v6, v2
	v_add_f32_e32 v6, 1.0, v5
	v_rcp_f32_e32 v77, v6
	v_add_f32_e32 v6, 1.0, v8
	v_rcp_f32_e32 v78, v6
	v_add_f32_e32 v6, 1.0, v9
	v_rcp_f32_e32 v79, v6
	v_mul_f32_e32 v7, v5, v77
	v_min_f32_e32 v11, 0x42a00000, v57
	v_mul_f32_e32 v5, v9, v79
	v_min_f32_e32 v9, 0x42a00000, v56
	v_exp_f32_e32 v9, v9
	v_exp_f32_e32 v13, v11
	v_min_f32_e32 v6, 0x42a00000, v55
	v_exp_f32_e32 v10, v6
	v_min_f32_e32 v49, 0x42a00000, v59
	v_add_f32_e32 v11, 1.0, v9
	v_exp_f32_e32 v50, v49
	v_rcp_f32_e32 v57, v11
	v_add_f32_e32 v11, 1.0, v13
	v_min_f32_e32 v49, 0x42a00000, v60
	v_rcp_f32_e32 v181, v11
	v_exp_f32_e32 v53, v49
	v_mul_f32_e32 v6, v8, v78
	v_add_f32_e32 v8, 1.0, v10
	v_min_f32_e32 v11, 0x42a00000, v58
	v_rcp_f32_e32 v8, v8
	v_exp_f32_e32 v48, v11
	v_add_f32_e32 v49, 1.0, v53
	v_rcp_f32_e32 v58, v49
	v_mul_f32_e32 v11, v10, v8
	v_mul_f32_e32 v10, v9, v57
	v_mul_f32_e32 v9, v13, v181
	v_add_f32_e32 v13, 1.0, v48
	v_min_f32_e32 v49, 0x42a00000, v61
	v_rcp_f32_e32 v59, v13
	v_exp_f32_e32 v54, v49
	v_add_f32_e32 v13, 1.0, v50
	v_rcp_f32_e32 v13, v13
	v_mul_f32_e32 v49, v48, v59
	v_mul_f32_e32 v48, v53, v58
	v_add_f32_e32 v53, 1.0, v54
	v_rcp_f32_e32 v60, v53
	v_min_f32_e32 v53, 0x42a00000, v62
	v_exp_f32_e32 v56, v53
	v_min_f32_e32 v53, 0x42a00000, v63
	v_exp_f32_e32 v62, v53
	v_add_f32_e32 v53, 1.0, v56
	v_rcp_f32_e32 v61, v53
	v_mul_f32_e32 v53, v54, v60
	v_add_f32_e32 v54, 1.0, v62
	v_rcp_f32_e32 v55, v54
	s_addk_i32 s25, 0xff9f
	v_mul_f32_e32 v4, v4, v76
	v_mul_f32_e32 v50, v50, v13
	v_mul_f32_e32 v54, v56, v61
	s_cmp_lt_i32 s25, s20
	v_mul_f32_e32 v56, v62, v55
	s_cbranch_scc1 .LBB0_680
	v_add_u32_e32 v62, s21, v178
	v_add_u32_e32 v62, 0x80, v62
	v_cmp_lt_i32_e32 vcc, 0, v62
	s_nop 1
	v_cndmask_b32_e32 v12, 1.0, v12, vcc
	v_cndmask_b32_e32 v75, 0, v75, vcc
	v_cmp_lt_i32_e32 vcc, 1, v62
	s_nop 1
	v_cndmask_b32_e32 v51, 1.0, v51, vcc
	v_cndmask_b32_e32 v52, 0, v52, vcc
	v_cmp_lt_i32_e32 vcc, 2, v62
	s_nop 1
	v_cndmask_b32_e32 v76, 1.0, v76, vcc
	v_cndmask_b32_e32 v4, 0, v4, vcc
	v_cmp_lt_i32_e32 vcc, 3, v62
	s_nop 1
	v_cndmask_b32_e32 v2, 1.0, v2, vcc
	v_cndmask_b32_e32 v3, 0, v3, vcc
	v_cmp_lt_i32_e32 vcc, 8, v62
	s_nop 1
	v_cndmask_b32_e32 v77, 1.0, v77, vcc
	v_cndmask_b32_e32 v7, 0, v7, vcc
	v_cmp_lt_i32_e32 vcc, 9, v62
	s_nop 1
	v_cndmask_b32_e32 v78, 1.0, v78, vcc
	v_cndmask_b32_e32 v6, 0, v6, vcc
	v_cmp_lt_i32_e32 vcc, 10, v62
	s_nop 1
	v_cndmask_b32_e32 v79, 1.0, v79, vcc
	v_cndmask_b32_e32 v5, 0, v5, vcc
	v_cmp_lt_i32_e32 vcc, 11, v62
	s_nop 1
	v_cndmask_b32_e32 v8, 1.0, v8, vcc
	v_cndmask_b32_e32 v11, 0, v11, vcc
	v_cmp_lt_i32_e32 vcc, 16, v62
	s_nop 1
	v_cndmask_b32_e32 v57, 1.0, v57, vcc
	v_cndmask_b32_e32 v10, 0, v10, vcc
	v_cmp_lt_i32_e32 vcc, 17, v62
	s_nop 1
	v_cndmask_b32_e32 v181, 1.0, v181, vcc
	v_cndmask_b32_e32 v9, 0, v9, vcc
	v_cmp_lt_i32_e32 vcc, 18, v62
	s_nop 1
	v_cndmask_b32_e32 v59, 1.0, v59, vcc
	v_cndmask_b32_e32 v49, 0, v49, vcc
	v_cmp_lt_i32_e32 vcc, 19, v62
	s_nop 1
	v_cndmask_b32_e32 v13, 1.0, v13, vcc
	v_cndmask_b32_e32 v50, 0, v50, vcc
	v_cmp_lt_i32_e32 vcc, 24, v62
	s_nop 1
	v_cndmask_b32_e32 v58, 1.0, v58, vcc
	v_cndmask_b32_e32 v48, 0, v48, vcc
	v_cmp_lt_i32_e32 vcc, 25, v62
	s_nop 1
	v_cndmask_b32_e32 v60, 1.0, v60, vcc
	v_cndmask_b32_e32 v53, 0, v53, vcc
	v_cmp_lt_i32_e32 vcc, 26, v62
	s_nop 1
	v_cndmask_b32_e32 v61, 1.0, v61, vcc
	v_cndmask_b32_e32 v54, 0, v54, vcc
	v_cmp_lt_i32_e32 vcc, 27, v62
	s_nop 1
	v_cndmask_b32_e32 v55, 1.0, v55, vcc
	v_cndmask_b32_e32 v56, 0, v56, vcc
